# KVQ phase start: per-row table loads waited at first consumer instead of right after issue
# speedup vs baseline: 1.0004x; 1.0004x over previous
.LBB0_275:
	s_andn2_b64 vcc, exec, s[4:5]
	s_cbranch_vccnz .LBB0_327
	s_movk_i32 s4, 0x100
	v_cmp_gt_i32_e64 s[4:5], s4, v234
	v_mov_b32_e32 v1, 0
	v_mov_b32_e32 v5, 0x358637bd
	s_and_saveexec_b64 s[10:11], s[4:5]
	s_cbranch_execz .LBB0_278
	v_readlane_b32 s12, v254, 49
	v_readlane_b32 s13, v254, 50
	v_lshl_add_u32 v2, s8, 8, v234
	s_load_dwordx16 s[44:59], s[12:13], 0x0
	v_ashrrev_i32_e32 v3, 31, v2
	v_lshlrev_b64 v[2:3], 2, v[2:3]
	v_lshl_add_u64 v[4:5], s[0:1], 0, v[2:3]
	v_add_co_u32_e32 v4, vcc, 0xa0000, v4
	s_waitcnt lgkmcnt(0)
	v_lshl_add_u64 v[2:3], s[46:47], 0, v[2:3]
	v_addc_co_u32_e32 v5, vcc, 0, v5, vcc
	global_load_dword v160, v[4:5], off
	s_nop 0
	global_load_dword v161, v[2:3], off
.LBB0_278:
	s_or_b64 exec, exec, s[10:11]
	v_bfe_i32 v3, v234, 27, 1
	v_lshlrev_b32_e32 v6, 4, v234
	v_lshrrev_b32_e32 v3, 22, v3
	v_ashrrev_i32_e32 v2, 31, v234
	v_add_u32_e32 v3, v6, v3
	v_lshrrev_b32_e32 v2, 26, v2
	v_and_b32_e32 v3, 0xfffffc00, v3
	s_sub_i32 s9, 2, s29
	v_add_u32_e32 v2, v234, v2
	v_sub_u32_e32 v3, v6, v3
	s_mul_hi_i32 s10, s9, 0x600000
	s_mul_i32 s9, s9, 0x600000
	v_ashrrev_i32_e32 v2, 6, v2
	v_lshrrev_b32_e32 v4, 4, v3
	s_add_u32 s9, s0, s9
	v_bitop3_b32 v4, v4, v3, 32 bitop3:0x6c
	v_lshlrev_b32_e32 v3, 3, v2
	s_addc_u32 s10, s1, s10
	v_and_b32_e32 v7, -16, v3
	v_ashrrev_i32_e32 v3, 31, v4
	s_add_u32 s40, s9, 0x500000
	v_lshrrev_b32_e32 v3, 26, v3
	s_addc_u32 s41, s10, 0
	s_ashr_i32 s9, s8, 31
	v_add_u32_e32 v8, v4, v3
	s_lshl_b64 s[10:11], s[8:9], 19
	v_ashrrev_i32_e32 v3, 6, v8
	v_and_b32_e32 v8, 0xc0, v8
	s_add_u32 s28, s80, s10
	v_sub_u32_e32 v4, v4, v8
	s_addc_u32 s29, s81, s11
	s_ashr_i32 s27, s26, 31
	v_lshlrev_b32_e32 v9, 5, v2
	v_ashrrev_i16_sdwa v4, v226, sext(v4) dst_sel:DWORD dst_unused:UNUSED_PAD src0_sel:DWORD src1_sel:BYTE_0
	s_lshl_b64 s[10:11], s[26:27], 19
	v_and_b32_e32 v9, 32, v9
	v_bfe_i32 v4, v4, 0, 16
	s_add_u32 s30, s40, s10
	v_add_u32_e32 v7, v3, v7
	v_and_b32_e32 v11, 3, v3
	s_mov_b32 s10, 0x1fffe0
	v_add_lshl_u32 v9, v9, v4, 1
	v_lshlrev_b32_e32 v8, 1, v7
	v_lshrrev_b32_e32 v10, 2, v7
	v_and_or_b32 v11, v7, s10, v11
	v_lshl_add_u32 v130, v7, 11, v9
	v_add_u32_e32 v7, 0x2000, v6
	v_ashrrev_i32_e32 v6, 31, v7
	v_lshrrev_b32_e32 v6, 22, v6
	v_and_b32_e32 v8, 24, v8
	v_and_b32_e32 v10, 4, v10
	v_add_u32_e32 v6, v7, v6
	v_or3_b32 v8, v11, v10, v8
	v_ashrrev_i32_e32 v6, 10, v6
	v_lshl_add_u32 v132, v8, 11, v9
	v_mul_i32_i24_e32 v8, 0x400, v6
	v_sub_u32_e32 v7, v7, v8
	v_lshrrev_b32_e32 v8, 4, v7
	v_bitop3_b32 v8, v8, v7, 32 bitop3:0x6c
	v_lshlrev_b32_e32 v7, 3, v6
	v_and_b32_e32 v9, -16, v7
	v_ashrrev_i32_e32 v7, 31, v8
	v_lshrrev_b32_e32 v7, 26, v7
	v_add_u32_e32 v10, v8, v7
	s_addc_u32 s31, s41, s11
	s_ashr_i32 s9, s14, 6
	v_ashrrev_i32_e32 v7, 6, v10
	v_and_b32_e32 v10, 0xc0, v10
	v_add_u32_e32 v9, v7, v9
	v_sub_u32_e32 v8, v8, v10
	s_lshl_b32 s27, s9, 10
	v_lshlrev_b32_e32 v11, 5, v6
	v_ashrrev_i16_sdwa v8, v226, sext(v8) dst_sel:DWORD dst_unused:UNUSED_PAD src0_sel:DWORD src1_sel:BYTE_0
	v_lshlrev_b32_e32 v10, 1, v9
	v_lshrrev_b32_e32 v12, 2, v9
	v_and_b32_e32 v13, 3, v7
	s_add_i32 s44, s27, 0
	v_and_b32_e32 v11, 32, v11
	v_bfe_i32 v8, v8, 0, 16
	v_and_b32_e32 v10, 24, v10
	v_and_b32_e32 v12, 4, v12
	v_and_or_b32 v13, v9, s10, v13
	s_add_i32 m0, s44, 0x10000
	v_or3_b32 v10, v13, v12, v10
	v_add_lshl_u32 v11, v11, v8, 1
	s_ashr_i32 s16, s14, 8
	global_load_lds_dwordx4 v132, s[30:31]
	s_add_i32 m0, s44, 0x12000
	v_lshl_add_u32 v136, v10, 11, v11
	s_add_u32 s10, s30, 0x40000
	global_load_lds_dwordx4 v136, s[30:31]
	s_addc_u32 s11, s31, 0
	s_add_i32 m0, s44, 0x14000
	s_add_i32 s45, s44, 0x2000
	global_load_lds_dwordx4 v132, s[10:11]
	s_add_i32 m0, s44, 0x16000
	v_lshl_add_u32 v134, v9, 11, v11
	global_load_lds_dwordx4 v136, s[10:11]
	s_mov_b32 m0, s44
	s_add_u32 s10, s28, 0x40000
	global_load_lds_dwordx4 v130, s[28:29]
	s_mov_b32 m0, s45
	s_addc_u32 s11, s29, 0
	s_add_i32 s43, s44, 0x4000
	global_load_lds_dwordx4 v134, s[28:29]
	s_mov_b32 m0, s43
	s_add_i32 s46, s44, 0x6000
	global_load_lds_dwordx4 v130, s[10:11]
	s_mov_b32 m0, s46
	s_cmp_eq_u32 s16, 1
	global_load_lds_dwordx4 v134, s[10:11]
	s_cselect_b64 s[10:11], -1, 0
	s_cmp_lg_u32 s16, 1
	s_cbranch_scc1 .LBB0_280
	s_barrier
.LBB0_280:
	v_mov_b32_e32 v133, v0
	v_lshl_add_u64 v[10:11], s[30:31], 0, v[132:133]
	v_mov_b32_e32 v137, v0
	v_lshl_add_u64 v[12:13], s[30:31], 0, v[136:137]
	v_mov_b32_e32 v131, v0
	s_add_i32 m0, s44, 0x18000
	v_lshl_add_u64 v[10:11], v[10:11], 0, s[96:97]
	v_lshl_add_u64 v[14:15], s[28:29], 0, v[130:131]
	v_mov_b32_e32 v135, v0
	s_waitcnt vmcnt(2)
	s_barrier
	global_load_lds_dwordx4 v[10:11], off
	v_lshl_add_u64 v[10:11], v[12:13], 0, s[96:97]
	s_add_i32 m0, s44, 0x1a000
	s_add_i32 s47, s44, 0x8000
	s_add_i32 s48, s44, 0xa000
	v_lshl_add_u64 v[16:17], s[28:29], 0, v[134:135]
	global_load_lds_dwordx4 v[10:11], off
	v_lshl_add_u64 v[10:11], v[14:15], 0, s[96:97]
	s_mov_b32 m0, s47
	s_add_u32 s12, s30, 0x40080
	global_load_lds_dwordx4 v[10:11], off
	v_lshl_add_u64 v[10:11], v[16:17], 0, s[96:97]
	s_mov_b32 m0, s48
	s_addc_u32 s13, s31, 0
	global_load_lds_dwordx4 v[10:11], off
	s_add_i32 m0, s44, 0x1c000
	v_lshl_add_u64 v[10:11], s[12:13], 0, v[132:133]
	global_load_lds_dwordx4 v[10:11], off
	v_lshl_add_u64 v[10:11], s[12:13], 0, v[136:137]
	s_add_i32 m0, s44, 0x1e000
	s_nop 0
	global_load_lds_dwordx4 v[10:11], off
	s_waitcnt vmcnt(6)
	s_barrier
	s_and_saveexec_b64 s[12:13], s[4:5]
	s_cbranch_execz .LBB0_282
	v_cvt_f32_u32_e32 v162, v160
	v_cvt_f32_i32_e32 v1, v161
	v_fmamk_f32 v5, v162, 0x34800000, v228
	v_rsq_f32_e32 v5, v5
	v_lshl_add_u32 v9, v234, 2, 0
	v_add_u32_e32 v9, 0x21000, v9
	ds_write2st64_b32 v9, v1, v5 offset1:4
